# mix_b tile staging batched (9 loads one wait) + mix_a sample-branch warm-up prefetch
# speedup vs baseline: 1.0326x; 1.0089x over previous
; #define LAS __attribute__((address_space(3)))
; __device__ __forceinline__ void mix_b_wave_jobs(Frame& F, int l) {
;     ...
;         int ln = lane; asm volatile("" : "+v"(ln));
; #pragma unroll
;         for (int i = 0; i < 9; ++i) {
;             const int p = ln + 64 * i;
;             if (p < 536) {
;                 const int rr = p >> 3, pc = p & 7, row = rr - 3;
;                 const bool okr = prompt ? (t0 + row >= 0) : (row >= 0);
;                 u32x4 v = *(const u32x4*)(BX + (size_t)(row0 + (okr ? row : 0)) * 512 + 64 * h + 8 * pc);
;                 if (!okr) v = (u32x4){0u, 0u, 0u, 0u};
;                 *(LAS u32x4*)(tile + rr * 72 + 8 * pc) = v;
;             }
;         }
.LBB0_58:
	v_mov_b32_e32 v1, v172
	s_movk_i32 s2, 0x218
	v_lshlrev_b32_e32 v0, 4, v1
	v_and_b32_e32 v128, 0x70, v0
	v_lshl_add_u64 v[2:3], s[40:41], 0, v[128:129]
	v_add_u32_e32 v0, s61, v128
	v_ashrrev_i32_e32 v8, 3, v1
	v_add_u32_e32 v4, -3, v8
	v_cmp_lt_i32_e32 vcc, 2, v8
	s_nop 1
	v_cndmask_b32_e64 v5, 0, 1, vcc
	v_cmp_lt_i32_e32 vcc, s20, v4
	s_nop 1
	v_cndmask_b32_e64 v6, 0, 1, vcc
	v_cndmask_b32_e64 v5, v6, v5, s[18:19]
	v_and_b32_e32 v5, 1, v5
	v_cmp_eq_u32_e32 vcc, 1, v5
	v_mad_u32_u24 v46, v8, s63, v0
	v_add_u32_e32 v9, s55, v4
	s_nop 0
	v_cndmask_b32_e32 v4, 0, v4, vcc
	v_add_u32_e32 v4, s55, v4
	v_lshl_add_u32 v4, v4, 10, v128
	v_lshl_add_u32 v9, v9, 10, v128
	s_mov_b64 s[22:23], vcc
	global_load_dwordx4 v[10:13], v4, s[40:41]
	v_add_u32_e32 v4, 0x2000, v9
	global_load_dwordx4 v[14:17], v4, s[40:41]
	v_add_u32_e32 v4, 0x4000, v9
	global_load_dwordx4 v[18:21], v4, s[40:41]
	v_add_u32_e32 v4, 0x6000, v9
	global_load_dwordx4 v[22:25], v4, s[40:41]
	v_add_u32_e32 v4, 0x8000, v9
	global_load_dwordx4 v[26:29], v4, s[40:41]
	v_add_u32_e32 v4, 0xa000, v9
	global_load_dwordx4 v[30:33], v4, s[40:41]
	v_add_u32_e32 v4, 0xc000, v9
	global_load_dwordx4 v[34:37], v4, s[40:41]
	v_add_u32_e32 v4, 0xe000, v9
	global_load_dwordx4 v[38:41], v4, s[40:41]
	v_cmp_gt_i32_e32 vcc, 24, v1
	s_and_saveexec_b64 s[2:3], vcc
	v_add_u32_e32 v4, 0x10000, v9
	global_load_dwordx4 v[42:45], v4, s[40:41]
	s_or_b64 exec, exec, s[2:3]
	s_waitcnt vmcnt(0)
	v_cndmask_b32_e64 v13, 0, v13, s[22:23]
	v_cndmask_b32_e64 v12, 0, v12, s[22:23]
	v_cndmask_b32_e64 v11, 0, v11, s[22:23]
	v_cndmask_b32_e64 v10, 0, v10, s[22:23]
	ds_write_b128 v46, v[10:13]
	ds_write_b128 v46, v[14:17] offset:1152
	ds_write_b128 v46, v[18:21] offset:2304
	ds_write_b128 v46, v[22:25] offset:3456
	ds_write_b128 v46, v[26:29] offset:4608
	ds_write_b128 v46, v[30:33] offset:5760
	ds_write_b128 v46, v[34:37] offset:6912
	ds_write_b128 v46, v[38:41] offset:8064
	v_cmp_gt_i32_e32 vcc, 24, v1
	s_and_saveexec_b64 s[2:3], vcc
	ds_write_b128 v46, v[42:45] offset:9216

; __device__ __forceinline__ void mix_a_wave_jobs(Frame& F, int l) {
;     ...
;             const int s0 = 2 * (tb - 1032); rowbase = MP + 8 * s0;
;             const float* st = F.in[I_SCA] + (size_t)l * NB_S * 30 * DA;
; #pragma unroll
;             for (int hs = 0; hs < 2; ++hs) {
;                 const int s = s0 + hs, rowS = MP + 8 * s;
; #pragma unroll
;                 for (int tt = 0; tt < 38; ++tt) {
;                     f32x2 v;
;                     if (tt < 30) v = __builtin_nontemporal_load((const f32x2*)(st + ((size_t)s * 30 + tt) * DA + c0));
;                     else { const unsigned rw = *(const unsigned*)(U + (size_t)(rowS + tt - 30) * 512 + c0); v = (f32x2){__uint_as_float(rw << 16), __uint_as_float(rw & 0xffff0000u)}; }
; #pragma unroll
;                     for (int t = 0; t < 8; ++t) { const int kk = tt - t; if (kk >= 0 && kk <= 30) a[8 * hs + t] += w[kk] * v; }
.LBB0_270:
	s_cmpk_gt_i32 s22, 0x407
	s_cbranch_scc0 .LBB0_272
	s_load_dwordx2 s[2:3], s[0:1], 0x10
	v_readlane_b32 s18, v254, 59
	s_mul_i32 s17, s18, 0x780000
	v_readlane_b32 s19, v254, 60
	s_movk_i32 s19, 0x3000
	s_waitcnt lgkmcnt(0)
	s_add_u32 s2, s2, s17
	s_addc_u32 s3, s3, s20
	v_lshl_add_u64 v[90:91], s[2:3], 0, v[128:129]
	v_mad_u64_u32 v[74:75], s[2:3], s21, v208, v[90:91]
	v_add_co_u32_e32 v214, vcc, 0x1000, v74
	s_nop 1
	v_addc_co_u32_e32 v215, vcc, 0, v75, vcc
	global_load_dwordx2 v[210:211], v[214:215], off offset:-4096
	global_load_dwordx2 v[210:211], v[214:215], off offset:-2048
	global_load_dwordx2 v[210:211], v[214:215], off
	global_load_dwordx2 v[210:211], v[214:215], off offset:2048
	v_add_co_u32_e32 v214, vcc, 0x2000, v214
	s_nop 1
	v_addc_co_u32_e32 v215, vcc, 0, v215, vcc
	global_load_dwordx2 v[210:211], v[214:215], off offset:-4096
	global_load_dwordx2 v[210:211], v[214:215], off offset:-2048
	global_load_dwordx2 v[210:211], v[214:215], off
	global_load_dwordx2 v[210:211], v[214:215], off offset:2048
	v_add_co_u32_e32 v214, vcc, 0x2000, v214
	s_nop 1
	v_addc_co_u32_e32 v215, vcc, 0, v215, vcc
	global_load_dwordx2 v[210:211], v[214:215], off offset:-4096
	global_load_dwordx2 v[210:211], v[214:215], off offset:-2048
	global_load_dwordx2 v[210:211], v[214:215], off
	global_load_dwordx2 v[210:211], v[214:215], off offset:2048
	v_add_co_u32_e32 v214, vcc, 0x2000, v214
	s_nop 1
	v_addc_co_u32_e32 v215, vcc, 0, v215, vcc
	global_load_dwordx2 v[210:211], v[214:215], off offset:-4096
	global_load_dwordx2 v[210:211], v[214:215], off offset:-2048
	global_load_dwordx2 v[210:211], v[214:215], off
	global_load_dwordx2 v[210:211], v[214:215], off offset:2048
	v_add_co_u32_e32 v214, vcc, 0x2000, v214
	s_nop 1
	v_addc_co_u32_e32 v215, vcc, 0, v215, vcc
	global_load_dwordx2 v[210:211], v[214:215], off offset:-4096
	global_load_dwordx2 v[210:211], v[214:215], off offset:-2048
	global_load_dwordx2 v[210:211], v[214:215], off
	global_load_dwordx2 v[210:211], v[214:215], off offset:2048
	v_add_co_u32_e32 v214, vcc, 0x2000, v214
	s_nop 1
	v_addc_co_u32_e32 v215, vcc, 0, v215, vcc
	global_load_dwordx2 v[210:211], v[214:215], off offset:-4096
	global_load_dwordx2 v[210:211], v[214:215], off offset:-2048
	global_load_dwordx2 v[210:211], v[214:215], off
	global_load_dwordx2 v[210:211], v[214:215], off offset:2048
	v_add_co_u32_e32 v214, vcc, 0x2000, v214
	s_nop 1
	v_addc_co_u32_e32 v215, vcc, 0, v215, vcc
	global_load_dwordx2 v[210:211], v[214:215], off offset:-4096
	global_load_dwordx2 v[210:211], v[214:215], off offset:-2048
	global_load_dwordx2 v[210:211], v[214:215], off
	global_load_dwordx2 v[210:211], v[214:215], off offset:2048
	v_add_co_u32_e32 v214, vcc, 0x2000, v214
	s_nop 1
	v_addc_co_u32_e32 v215, vcc, 0, v215, vcc
	global_load_dwordx2 v[210:211], v[214:215], off offset:-4096
	global_load_dwordx2 v[210:211], v[214:215], off offset:-2048
	global_load_dwordx2 v[210:211], v[214:215], off
	global_load_dwordx2 v[210:211], v[214:215], off offset:2048
	v_add_co_u32_e32 v214, vcc, 0x2000, v214
	s_nop 1
	v_addc_co_u32_e32 v215, vcc, 0, v215, vcc
	global_load_dwordx2 v[210:211], v[214:215], off offset:-4096
	global_load_dwordx2 v[210:211], v[214:215], off offset:-2048
	global_load_dwordx2 v[210:211], v[214:215], off
	global_load_dwordx2 v[210:211], v[214:215], off offset:2048
	v_add_co_u32_e32 v214, vcc, 0x2000, v214
	s_nop 1
	v_addc_co_u32_e32 v215, vcc, 0, v215, vcc
	global_load_dwordx2 v[210:211], v[214:215], off offset:-4096
	global_load_dwordx2 v[210:211], v[214:215], off offset:-2048
	global_load_dwordx2 v[210:211], v[214:215], off
	global_load_dwordx2 v[210:211], v[214:215], off offset:2048
	v_add_co_u32_e32 v214, vcc, 0x2000, v214
	s_nop 1
	v_addc_co_u32_e32 v215, vcc, 0, v215, vcc
	global_load_dwordx2 v[210:211], v[214:215], off offset:-4096
	global_load_dwordx2 v[210:211], v[214:215], off offset:-2048
	global_load_dwordx2 v[210:211], v[214:215], off
	global_load_dwordx2 v[210:211], v[214:215], off offset:2048
	v_add_co_u32_e32 v214, vcc, 0x2000, v214
	s_nop 1
	v_addc_co_u32_e32 v215, vcc, 0, v215, vcc
	global_load_dwordx2 v[210:211], v[214:215], off offset:-4096
	global_load_dwordx2 v[210:211], v[214:215], off offset:-2048
	global_load_dwordx2 v[210:211], v[214:215], off
	global_load_dwordx2 v[210:211], v[214:215], off offset:2048
	v_add_co_u32_e32 v214, vcc, 0x2000, v214
	s_nop 1
	v_addc_co_u32_e32 v215, vcc, 0, v215, vcc
	global_load_dwordx2 v[210:211], v[214:215], off offset:-4096
	global_load_dwordx2 v[210:211], v[214:215], off offset:-2048
	global_load_dwordx2 v[210:211], v[214:215], off
	global_load_dwordx2 v[210:211], v[214:215], off offset:2048
	v_add_co_u32_e32 v214, vcc, 0x2000, v214
	s_nop 1
	v_addc_co_u32_e32 v215, vcc, 0, v215, vcc
	global_load_dwordx2 v[210:211], v[214:215], off offset:-4096
	global_load_dwordx2 v[210:211], v[214:215], off offset:-2048
	global_load_dwordx2 v[210:211], v[214:215], off
	global_load_dwordx2 v[210:211], v[214:215], off offset:2048
	v_add_co_u32_e32 v214, vcc, 0x2000, v214
	s_nop 1
	v_addc_co_u32_e32 v215, vcc, 0, v215, vcc
	global_load_dwordx2 v[210:211], v[214:215], off offset:-4096
	global_load_dwordx2 v[210:211], v[214:215], off offset:-2048
	global_load_dwordx2 v[210:211], v[214:215], off
	global_load_dwordx2 v[210:211], v[214:215], off offset:2048
	s_add_i32 s2, s16, -15
	s_mov_b32 s3, s89
	s_lshl_b64 s[2:3], s[2:3], 10
	v_lshl_add_u64 v[214:215], v[70:71], 0, s[2:3]
	v_add_co_u32_e32 v214, vcc, 0x1000, v214
	s_nop 1
	v_addc_co_u32_e32 v215, vcc, 0, v215, vcc
	s_waitcnt vmcnt(24)
; __device__ __forceinline__ void mix_a_wave_jobs(Frame& F, int l) {
;     ...
; #pragma unroll
;             for (int hs = 0; hs < 2; ++hs) {
;                 const int s = s0 + hs, rowS = MP + 8 * s;
; #pragma unroll
;                 for (int tt = 0; tt < 38; ++tt) {
;                     f32x2 v;
;                     if (tt < 30) v = __builtin_nontemporal_load((const f32x2*)(st + ((size_t)s * 30 + tt) * DA + c0));
;                     else { const unsigned rw = *(const unsigned*)(U + (size_t)(rowS + tt - 30) * 512 + c0); v = (f32x2){__uint_as_float(rw << 16), __uint_as_float(rw & 0xffff0000u)}; }
; #pragma unroll
;                     for (int t = 0; t < 8; ++t) { const int kk = tt - t; if (kk >= 0 && kk <= 30) a[8 * hs + t] += w[kk] * v; }
;                 }
;             }
	global_load_dword v212, v[214:215], off offset:-4096
	global_load_dword v212, v[214:215], off offset:-3072
	global_load_dword v212, v[214:215], off offset:-2048
	global_load_dword v212, v[214:215], off offset:-1024
	global_load_dword v212, v[214:215], off
	global_load_dword v212, v[214:215], off offset:1024
	global_load_dword v212, v[214:215], off offset:2048
	global_load_dword v212, v[214:215], off offset:3072
	v_add_co_u32_e32 v214, vcc, 0x2000, v214
	s_nop 1
	v_addc_co_u32_e32 v215, vcc, 0, v215, vcc
	global_load_dword v212, v[214:215], off offset:-4096
	global_load_dword v212, v[214:215], off offset:-3072
	global_load_dword v212, v[214:215], off offset:-2048
	global_load_dword v212, v[214:215], off offset:-1024
	global_load_dword v212, v[214:215], off
	global_load_dword v212, v[214:215], off offset:1024
	global_load_dword v212, v[214:215], off offset:2048
	global_load_dword v212, v[214:215], off offset:3072
	v_add_co_u32_e32 v80, vcc, s85, v74
	s_movk_i32 s17, 0x2000
	s_nop 0
	v_addc_co_u32_e32 v81, vcc, 0, v75, vcc
	v_add_co_u32_e32 v82, vcc, s17, v74
	global_load_dwordx2 v[76:77], v[74:75], off nt
	global_load_dwordx2 v[78:79], v[74:75], off offset:2048 nt
	v_addc_co_u32_e32 v83, vcc, 0, v75, vcc
	v_add_co_u32_e32 v88, vcc, s19, v74
	global_load_dwordx2 v[84:85], v[82:83], off offset:-4096 nt
	s_nop 0
	v_addc_co_u32_e32 v89, vcc, 0, v75, vcc
	s_movk_i32 s18, 0x4000
	global_load_dwordx2 v[80:81], v[80:81], off offset:2048 nt
	v_add_co_u32_e32 v92, vcc, s18, v74
	global_load_dwordx2 v[86:87], v[82:83], off nt
	s_nop 0
	v_addc_co_u32_e32 v93, vcc, 0, v75, vcc
	global_load_dwordx2 v[88:89], v[88:89], off offset:2048 nt
	s_movk_i32 s23, 0x5000
	global_load_dwordx2 v[96:97], v[92:93], off nt
	global_load_dwordx2 v[94:95], v[92:93], off offset:-4096 nt
	s_movk_i32 s24, 0x6000
	global_load_dwordx2 v[82:83], v[82:83], off offset:2048 nt
	s_movk_i32 s25, 0x7000
	global_load_dwordx2 v[92:93], v[92:93], off offset:2048 nt
	s_mov_b32 s26, 0x8000
	s_mov_b32 s27, 0x9000
	s_mov_b32 s28, 0xa000
	s_mov_b32 s29, 0xb000
	s_mov_b32 s30, 0xc000
	s_mov_b32 s31, 0xd000
	s_mov_b32 s34, 0xe000
	s_add_i32 s88, s16, -15
	s_lshl_b64 s[2:3], s[88:89], 10
	s_waitcnt vmcnt(9)
	v_pk_fma_f32 v[76:77], v[2:3], v[76:77], v[64:65]
	s_waitcnt vmcnt(8)
	v_pk_fma_f32 v[76:77], v[4:5], v[78:79], v[76:77]
	v_pk_fma_f32 v[78:79], v[2:3], v[78:79], v[64:65]
	s_waitcnt vmcnt(7)
	v_pk_fma_f32 v[76:77], v[6:7], v[84:85], v[76:77]
	v_pk_fma_f32 v[78:79], v[4:5], v[84:85], v[78:79]
	v_pk_fma_f32 v[84:85], v[2:3], v[84:85], v[64:65]
	s_waitcnt vmcnt(6)
	v_pk_fma_f32 v[76:77], v[8:9], v[80:81], v[76:77]
	v_pk_fma_f32 v[78:79], v[6:7], v[80:81], v[78:79]
	v_pk_fma_f32 v[84:85], v[4:5], v[80:81], v[84:85]
	v_pk_fma_f32 v[80:81], v[2:3], v[80:81], v[64:65]
	s_waitcnt vmcnt(5)
	v_pk_fma_f32 v[76:77], v[10:11], v[86:87], v[76:77]
	v_pk_fma_f32 v[78:79], v[8:9], v[86:87], v[78:79]
	v_pk_fma_f32 v[84:85], v[6:7], v[86:87], v[84:85]
	v_pk_fma_f32 v[80:81], v[4:5], v[86:87], v[80:81]
	v_pk_fma_f32 v[86:87], v[2:3], v[86:87], v[64:65]
	s_waitcnt vmcnt(1)
	v_pk_fma_f32 v[76:77], v[12:13], v[82:83], v[76:77]
	v_pk_fma_f32 v[78:79], v[10:11], v[82:83], v[78:79]
	v_pk_fma_f32 v[84:85], v[8:9], v[82:83], v[84:85]
	v_pk_fma_f32 v[80:81], v[6:7], v[82:83], v[80:81]
	v_pk_fma_f32 v[86:87], v[4:5], v[82:83], v[86:87]
	v_pk_fma_f32 v[82:83], v[2:3], v[82:83], v[64:65]
	v_pk_fma_f32 v[76:77], v[14:15], v[94:95], v[76:77]
	v_pk_fma_f32 v[78:79], v[12:13], v[94:95], v[78:79]
	v_pk_fma_f32 v[84:85], v[10:11], v[94:95], v[84:85]
	v_pk_fma_f32 v[80:81], v[8:9], v[94:95], v[80:81]
	v_pk_fma_f32 v[86:87], v[6:7], v[94:95], v[86:87]
	v_pk_fma_f32 v[82:83], v[4:5], v[94:95], v[82:83]
	v_pk_fma_f32 v[94:95], v[2:3], v[94:95], v[64:65]
	v_pk_fma_f32 v[76:77], v[16:17], v[88:89], v[76:77]
	v_pk_fma_f32 v[78:79], v[14:15], v[88:89], v[78:79]
	v_pk_fma_f32 v[84:85], v[12:13], v[88:89], v[84:85]
	v_pk_fma_f32 v[80:81], v[10:11], v[88:89], v[80:81]
	v_pk_fma_f32 v[86:87], v[8:9], v[88:89], v[86:87]
	v_pk_fma_f32 v[82:83], v[6:7], v[88:89], v[82:83]
	v_pk_fma_f32 v[94:95], v[4:5], v[88:89], v[94:95]
	v_pk_fma_f32 v[88:89], v[2:3], v[88:89], v[64:65]
	v_pk_fma_f32 v[76:77], v[18:19], v[96:97], v[76:77]
	v_pk_fma_f32 v[78:79], v[16:17], v[96:97], v[78:79]
	v_pk_fma_f32 v[84:85], v[14:15], v[96:97], v[84:85]
	v_pk_fma_f32 v[80:81], v[12:13], v[96:97], v[80:81]
	v_pk_fma_f32 v[86:87], v[10:11], v[96:97], v[86:87]
	v_pk_fma_f32 v[82:83], v[8:9], v[96:97], v[82:83]
	v_pk_fma_f32 v[94:95], v[6:7], v[96:97], v[94:95]
	v_pk_fma_f32 v[88:89], v[4:5], v[96:97], v[88:89]
	s_waitcnt vmcnt(0)
	v_pk_fma_f32 v[76:77], v[20:21], v[92:93], v[76:77]
	v_pk_fma_f32 v[78:79], v[18:19], v[92:93], v[78:79]
	v_pk_fma_f32 v[84:85], v[16:17], v[92:93], v[84:85]
	v_pk_fma_f32 v[80:81], v[14:15], v[92:93], v[80:81]
	v_pk_fma_f32 v[86:87], v[12:13], v[92:93], v[86:87]
	v_pk_fma_f32 v[82:83], v[10:11], v[92:93], v[82:83]
	v_pk_fma_f32 v[94:95], v[8:9], v[92:93], v[94:95]
	v_pk_fma_f32 v[88:89], v[6:7], v[92:93], v[88:89]
	v_add_co_u32_e32 v92, vcc, s23, v74
	s_nop 1
	v_addc_co_u32_e32 v93, vcc, 0, v75, vcc
	v_add_co_u32_e32 v96, vcc, s24, v74
	global_load_dwordx2 v[92:93], v[92:93], off offset:2048 nt
	s_nop 0
	v_addc_co_u32_e32 v97, vcc, 0, v75, vcc
	global_load_dwordx2 v[98:99], v[96:97], off offset:-4096 nt
	s_waitcnt vmcnt(0)
; __device__ __forceinline__ void mix_a_wave_jobs(Frame& F, int l) {
;     ...
;                 for (int tt = 0; tt < 38; ++tt) {
;                     f32x2 v;
;                     if (tt < 30) v = __builtin_nontemporal_load((const f32x2*)(st + ((size_t)s * 30 + tt) * DA + c0));
;                     else { const unsigned rw = *(const unsigned*)(U + (size_t)(rowS + tt - 30) * 512 + c0); v = (f32x2){__uint_as_float(rw << 16), __uint_as_float(rw & 0xffff0000u)}; }
; #pragma unroll
;                     for (int t = 0; t < 8; ++t) { const int kk = tt - t; if (kk >= 0 && kk <= 30) a[8 * hs + t] += w[kk] * v; }
	v_pk_fma_f32 v[76:77], v[22:23], v[98:99], v[76:77]
	v_pk_fma_f32 v[78:79], v[20:21], v[98:99], v[78:79]
	v_pk_fma_f32 v[84:85], v[18:19], v[98:99], v[84:85]
	v_pk_fma_f32 v[80:81], v[16:17], v[98:99], v[80:81]
	v_pk_fma_f32 v[86:87], v[14:15], v[98:99], v[86:87]
	v_pk_fma_f32 v[82:83], v[12:13], v[98:99], v[82:83]
	v_pk_fma_f32 v[94:95], v[10:11], v[98:99], v[94:95]
	v_pk_fma_f32 v[88:89], v[8:9], v[98:99], v[88:89]
	v_pk_fma_f32 v[76:77], v[24:25], v[92:93], v[76:77]
	v_pk_fma_f32 v[78:79], v[22:23], v[92:93], v[78:79]
	v_pk_fma_f32 v[84:85], v[20:21], v[92:93], v[84:85]
	v_pk_fma_f32 v[80:81], v[18:19], v[92:93], v[80:81]
	v_pk_fma_f32 v[86:87], v[16:17], v[92:93], v[86:87]
	v_pk_fma_f32 v[82:83], v[14:15], v[92:93], v[82:83]
	v_pk_fma_f32 v[94:95], v[12:13], v[92:93], v[94:95]
	v_pk_fma_f32 v[88:89], v[10:11], v[92:93], v[88:89]
	global_load_dwordx2 v[92:93], v[96:97], off nt
	s_waitcnt vmcnt(0)
	v_pk_fma_f32 v[76:77], v[26:27], v[92:93], v[76:77]
	v_pk_fma_f32 v[78:79], v[24:25], v[92:93], v[78:79]
	v_pk_fma_f32 v[84:85], v[22:23], v[92:93], v[84:85]
	v_pk_fma_f32 v[80:81], v[20:21], v[92:93], v[80:81]
	v_pk_fma_f32 v[86:87], v[18:19], v[92:93], v[86:87]
	v_pk_fma_f32 v[82:83], v[16:17], v[92:93], v[82:83]
	v_pk_fma_f32 v[94:95], v[14:15], v[92:93], v[94:95]
	v_pk_fma_f32 v[88:89], v[12:13], v[92:93], v[88:89]
	global_load_dwordx2 v[92:93], v[96:97], off offset:2048 nt
	s_waitcnt vmcnt(0)
	v_pk_fma_f32 v[96:97], v[28:29], v[92:93], v[76:77]
	v_pk_fma_f32 v[78:79], v[26:27], v[92:93], v[78:79]
	v_pk_fma_f32 v[84:85], v[24:25], v[92:93], v[84:85]
	v_pk_fma_f32 v[80:81], v[22:23], v[92:93], v[80:81]
	v_pk_fma_f32 v[86:87], v[20:21], v[92:93], v[86:87]
	v_pk_fma_f32 v[82:83], v[18:19], v[92:93], v[82:83]
	v_pk_fma_f32 v[94:95], v[16:17], v[92:93], v[94:95]
	v_pk_fma_f32 v[88:89], v[14:15], v[92:93], v[88:89]
	v_add_co_u32_e32 v92, vcc, s25, v74
	s_nop 1
	v_addc_co_u32_e32 v93, vcc, 0, v75, vcc
	v_add_co_u32_e32 v76, vcc, s26, v74
	global_load_dwordx2 v[92:93], v[92:93], off offset:2048 nt
	s_nop 0
	v_addc_co_u32_e32 v77, vcc, 0, v75, vcc
	global_load_dwordx2 v[98:99], v[76:77], off offset:-4096 nt
	s_waitcnt vmcnt(0)
	v_pk_fma_f32 v[96:97], v[30:31], v[98:99], v[96:97]
	v_pk_fma_f32 v[78:79], v[28:29], v[98:99], v[78:79]
	v_pk_fma_f32 v[84:85], v[26:27], v[98:99], v[84:85]
	v_pk_fma_f32 v[80:81], v[24:25], v[98:99], v[80:81]
	v_pk_fma_f32 v[86:87], v[22:23], v[98:99], v[86:87]
	v_pk_fma_f32 v[82:83], v[20:21], v[98:99], v[82:83]
	v_pk_fma_f32 v[94:95], v[18:19], v[98:99], v[94:95]
	v_pk_fma_f32 v[88:89], v[16:17], v[98:99], v[88:89]
	v_pk_fma_f32 v[96:97], v[32:33], v[92:93], v[96:97]
	v_pk_fma_f32 v[78:79], v[30:31], v[92:93], v[78:79]
	v_pk_fma_f32 v[84:85], v[28:29], v[92:93], v[84:85]
	v_pk_fma_f32 v[80:81], v[26:27], v[92:93], v[80:81]
	v_pk_fma_f32 v[86:87], v[24:25], v[92:93], v[86:87]
	v_pk_fma_f32 v[82:83], v[22:23], v[92:93], v[82:83]
	v_pk_fma_f32 v[94:95], v[20:21], v[92:93], v[94:95]
	v_pk_fma_f32 v[88:89], v[18:19], v[92:93], v[88:89]
	global_load_dwordx2 v[92:93], v[76:77], off nt
	s_waitcnt vmcnt(0)
	v_pk_fma_f32 v[96:97], v[34:35], v[92:93], v[96:97]
	global_load_dwordx2 v[76:77], v[76:77], off offset:2048 nt
	v_pk_fma_f32 v[78:79], v[32:33], v[92:93], v[78:79]
	v_pk_fma_f32 v[84:85], v[30:31], v[92:93], v[84:85]
	v_pk_fma_f32 v[80:81], v[28:29], v[92:93], v[80:81]
	v_pk_fma_f32 v[86:87], v[26:27], v[92:93], v[86:87]
	v_pk_fma_f32 v[82:83], v[24:25], v[92:93], v[82:83]
	v_pk_fma_f32 v[94:95], v[22:23], v[92:93], v[94:95]
	v_pk_fma_f32 v[88:89], v[20:21], v[92:93], v[88:89]
	s_waitcnt vmcnt(0)
	v_pk_fma_f32 v[92:93], v[36:37], v[76:77], v[96:97]
	v_pk_fma_f32 v[78:79], v[34:35], v[76:77], v[78:79]
	v_pk_fma_f32 v[84:85], v[32:33], v[76:77], v[84:85]
	v_pk_fma_f32 v[80:81], v[30:31], v[76:77], v[80:81]
	v_pk_fma_f32 v[86:87], v[28:29], v[76:77], v[86:87]
	v_pk_fma_f32 v[82:83], v[26:27], v[76:77], v[82:83]
	v_pk_fma_f32 v[94:95], v[24:25], v[76:77], v[94:95]
	v_pk_fma_f32 v[76:77], v[22:23], v[76:77], v[88:89]
	v_add_co_u32_e32 v88, vcc, s27, v74
	s_nop 1
	v_addc_co_u32_e32 v89, vcc, 0, v75, vcc
	v_add_co_u32_e32 v96, vcc, s28, v74
	global_load_dwordx2 v[88:89], v[88:89], off offset:2048 nt
	s_nop 0
	v_addc_co_u32_e32 v97, vcc, 0, v75, vcc
	global_load_dwordx2 v[98:99], v[96:97], off offset:-4096 nt
	s_waitcnt vmcnt(0)
	v_pk_fma_f32 v[92:93], v[38:39], v[98:99], v[92:93]
	v_pk_fma_f32 v[78:79], v[36:37], v[98:99], v[78:79]
	v_pk_fma_f32 v[84:85], v[34:35], v[98:99], v[84:85]
	v_pk_fma_f32 v[80:81], v[32:33], v[98:99], v[80:81]
	v_pk_fma_f32 v[86:87], v[30:31], v[98:99], v[86:87]
	v_pk_fma_f32 v[82:83], v[28:29], v[98:99], v[82:83]
	v_pk_fma_f32 v[94:95], v[26:27], v[98:99], v[94:95]
	v_pk_fma_f32 v[76:77], v[24:25], v[98:99], v[76:77]
	v_pk_fma_f32 v[92:93], v[40:41], v[88:89], v[92:93]
	v_pk_fma_f32 v[78:79], v[38:39], v[88:89], v[78:79]
	v_pk_fma_f32 v[84:85], v[36:37], v[88:89], v[84:85]
	v_pk_fma_f32 v[80:81], v[34:35], v[88:89], v[80:81]
	v_pk_fma_f32 v[86:87], v[32:33], v[88:89], v[86:87]
	v_pk_fma_f32 v[82:83], v[30:31], v[88:89], v[82:83]
	v_pk_fma_f32 v[94:95], v[28:29], v[88:89], v[94:95]
	v_pk_fma_f32 v[76:77], v[26:27], v[88:89], v[76:77]
	global_load_dwordx2 v[88:89], v[96:97], off nt
	s_waitcnt vmcnt(0)
	v_pk_fma_f32 v[92:93], v[42:43], v[88:89], v[92:93]
	v_pk_fma_f32 v[78:79], v[40:41], v[88:89], v[78:79]
	v_pk_fma_f32 v[84:85], v[38:39], v[88:89], v[84:85]
	v_pk_fma_f32 v[80:81], v[36:37], v[88:89], v[80:81]
	v_pk_fma_f32 v[86:87], v[34:35], v[88:89], v[86:87]
	v_pk_fma_f32 v[82:83], v[32:33], v[88:89], v[82:83]
	v_pk_fma_f32 v[94:95], v[30:31], v[88:89], v[94:95]
	v_pk_fma_f32 v[76:77], v[28:29], v[88:89], v[76:77]
	global_load_dwordx2 v[88:89], v[96:97], off offset:2048 nt
	v_add_co_u32_e32 v96, vcc, s29, v74
	s_waitcnt vmcnt(0)
; __device__ __forceinline__ void mix_a_wave_jobs(Frame& F, int l) {
;     ...
;                 for (int tt = 0; tt < 38; ++tt) {
;                     f32x2 v;
;                     if (tt < 30) v = __builtin_nontemporal_load((const f32x2*)(st + ((size_t)s * 30 + tt) * DA + c0));
;                     else { const unsigned rw = *(const unsigned*)(U + (size_t)(rowS + tt - 30) * 512 + c0); v = (f32x2){__uint_as_float(rw << 16), __uint_as_float(rw & 0xffff0000u)}; }
; #pragma unroll
;                     for (int t = 0; t < 8; ++t) { const int kk = tt - t; if (kk >= 0 && kk <= 30) a[8 * hs + t] += w[kk] * v; }
	v_pk_fma_f32 v[92:93], v[44:45], v[88:89], v[92:93]
	v_addc_co_u32_e32 v97, vcc, 0, v75, vcc
	v_pk_fma_f32 v[78:79], v[42:43], v[88:89], v[78:79]
	v_pk_fma_f32 v[84:85], v[40:41], v[88:89], v[84:85]
	v_pk_fma_f32 v[80:81], v[38:39], v[88:89], v[80:81]
	v_pk_fma_f32 v[86:87], v[36:37], v[88:89], v[86:87]
	v_pk_fma_f32 v[82:83], v[34:35], v[88:89], v[82:83]
	v_pk_fma_f32 v[94:95], v[32:33], v[88:89], v[94:95]
	v_pk_fma_f32 v[88:89], v[30:31], v[88:89], v[76:77]
	v_add_co_u32_e32 v76, vcc, s30, v74
	global_load_dwordx2 v[96:97], v[96:97], off offset:2048 nt
	s_nop 0
	v_addc_co_u32_e32 v77, vcc, 0, v75, vcc
	global_load_dwordx2 v[98:99], v[76:77], off offset:-4096 nt
	s_waitcnt vmcnt(0)
	v_pk_fma_f32 v[92:93], v[46:47], v[98:99], v[92:93]
	v_pk_fma_f32 v[78:79], v[44:45], v[98:99], v[78:79]
	v_pk_fma_f32 v[84:85], v[42:43], v[98:99], v[84:85]
	v_pk_fma_f32 v[80:81], v[40:41], v[98:99], v[80:81]
	v_pk_fma_f32 v[86:87], v[38:39], v[98:99], v[86:87]
	v_pk_fma_f32 v[82:83], v[36:37], v[98:99], v[82:83]
	v_pk_fma_f32 v[94:95], v[34:35], v[98:99], v[94:95]
	v_pk_fma_f32 v[88:89], v[32:33], v[98:99], v[88:89]
	v_pk_fma_f32 v[92:93], v[48:49], v[96:97], v[92:93]
	v_pk_fma_f32 v[78:79], v[46:47], v[96:97], v[78:79]
	v_pk_fma_f32 v[84:85], v[44:45], v[96:97], v[84:85]
	v_pk_fma_f32 v[80:81], v[42:43], v[96:97], v[80:81]
	v_pk_fma_f32 v[86:87], v[40:41], v[96:97], v[86:87]
	v_pk_fma_f32 v[82:83], v[38:39], v[96:97], v[82:83]
	v_pk_fma_f32 v[94:95], v[36:37], v[96:97], v[94:95]
	v_pk_fma_f32 v[88:89], v[34:35], v[96:97], v[88:89]
	global_load_dwordx2 v[96:97], v[76:77], off nt
	s_waitcnt vmcnt(0)
	v_pk_fma_f32 v[92:93], v[50:51], v[96:97], v[92:93]
	global_load_dwordx2 v[76:77], v[76:77], off offset:2048 nt
	v_pk_fma_f32 v[78:79], v[48:49], v[96:97], v[78:79]
	v_pk_fma_f32 v[84:85], v[46:47], v[96:97], v[84:85]
	v_pk_fma_f32 v[80:81], v[44:45], v[96:97], v[80:81]
	v_pk_fma_f32 v[86:87], v[42:43], v[96:97], v[86:87]
	v_pk_fma_f32 v[82:83], v[40:41], v[96:97], v[82:83]
	v_pk_fma_f32 v[94:95], v[38:39], v[96:97], v[94:95]
	v_pk_fma_f32 v[88:89], v[36:37], v[96:97], v[88:89]
	s_waitcnt vmcnt(0)
	v_pk_fma_f32 v[92:93], v[52:53], v[76:77], v[92:93]
	v_pk_fma_f32 v[78:79], v[50:51], v[76:77], v[78:79]
	v_pk_fma_f32 v[84:85], v[48:49], v[76:77], v[84:85]
	v_pk_fma_f32 v[80:81], v[46:47], v[76:77], v[80:81]
	v_pk_fma_f32 v[86:87], v[44:45], v[76:77], v[86:87]
	v_pk_fma_f32 v[82:83], v[42:43], v[76:77], v[82:83]
	v_pk_fma_f32 v[94:95], v[40:41], v[76:77], v[94:95]
	v_pk_fma_f32 v[76:77], v[38:39], v[76:77], v[88:89]
	v_add_co_u32_e32 v88, vcc, s31, v74
	s_nop 1
	v_addc_co_u32_e32 v89, vcc, 0, v75, vcc
	v_add_co_u32_e32 v74, vcc, s34, v74
	global_load_dwordx2 v[88:89], v[88:89], off offset:2048 nt
	s_nop 0
	v_addc_co_u32_e32 v75, vcc, 0, v75, vcc
	global_load_dwordx2 v[96:97], v[74:75], off offset:-4096 nt
	s_waitcnt vmcnt(0)
	v_pk_fma_f32 v[92:93], v[54:55], v[96:97], v[92:93]
	v_pk_fma_f32 v[78:79], v[52:53], v[96:97], v[78:79]
	v_pk_fma_f32 v[84:85], v[50:51], v[96:97], v[84:85]
	v_pk_fma_f32 v[80:81], v[48:49], v[96:97], v[80:81]
	v_pk_fma_f32 v[86:87], v[46:47], v[96:97], v[86:87]
	v_pk_fma_f32 v[82:83], v[44:45], v[96:97], v[82:83]
	v_pk_fma_f32 v[94:95], v[42:43], v[96:97], v[94:95]
	v_pk_fma_f32 v[76:77], v[40:41], v[96:97], v[76:77]
	v_pk_fma_f32 v[92:93], v[56:57], v[88:89], v[92:93]
	v_pk_fma_f32 v[78:79], v[54:55], v[88:89], v[78:79]
	v_pk_fma_f32 v[84:85], v[52:53], v[88:89], v[84:85]
	v_pk_fma_f32 v[80:81], v[50:51], v[88:89], v[80:81]
	v_pk_fma_f32 v[86:87], v[48:49], v[88:89], v[86:87]
	v_pk_fma_f32 v[82:83], v[46:47], v[88:89], v[82:83]
	v_pk_fma_f32 v[94:95], v[44:45], v[88:89], v[94:95]
	v_pk_fma_f32 v[76:77], v[42:43], v[88:89], v[76:77]
	global_load_dwordx2 v[88:89], v[74:75], off nt
	s_waitcnt vmcnt(0)
	v_pk_fma_f32 v[92:93], v[58:59], v[88:89], v[92:93]
	global_load_dwordx2 v[74:75], v[74:75], off offset:2048 nt
	v_pk_fma_f32 v[78:79], v[56:57], v[88:89], v[78:79]
	v_pk_fma_f32 v[84:85], v[54:55], v[88:89], v[84:85]
	v_pk_fma_f32 v[80:81], v[52:53], v[88:89], v[80:81]
	v_pk_fma_f32 v[86:87], v[50:51], v[88:89], v[86:87]
	v_pk_fma_f32 v[82:83], v[48:49], v[88:89], v[82:83]
	v_pk_fma_f32 v[94:95], v[46:47], v[88:89], v[94:95]
	v_pk_fma_f32 v[76:77], v[44:45], v[88:89], v[76:77]
	s_waitcnt vmcnt(0)
	v_pk_fma_f32 v[88:89], v[60:61], v[74:75], v[92:93]
	v_pk_fma_f32 v[78:79], v[58:59], v[74:75], v[78:79]
	v_pk_fma_f32 v[84:85], v[56:57], v[74:75], v[84:85]
	v_pk_fma_f32 v[80:81], v[54:55], v[74:75], v[80:81]
	v_pk_fma_f32 v[86:87], v[52:53], v[74:75], v[86:87]
	v_pk_fma_f32 v[82:83], v[50:51], v[74:75], v[82:83]
	v_pk_fma_f32 v[92:93], v[48:49], v[74:75], v[94:95]
	v_pk_fma_f32 v[76:77], v[46:47], v[74:75], v[76:77]
	v_lshl_add_u64 v[74:75], v[70:71], 0, s[2:3]
	global_load_dword v74, v[74:75], off
	s_add_i32 s2, s16, -14
	s_mov_b32 s3, s89
	s_lshl_b64 s[2:3], s[2:3], 10
	s_waitcnt vmcnt(0)
	v_lshlrev_b32_e32 v94, 16, v74
	v_and_b32_e32 v95, 0xffff0000, v74
	v_pk_fma_f32 v[74:75], v[62:63], v[94:95], v[88:89]
	v_pk_fma_f32 v[88:89], v[50:51], v[94:95], v[92:93]
	v_pk_fma_f32 v[92:93], v[48:49], v[94:95], v[76:77]
	v_lshl_add_u64 v[76:77], v[70:71], 0, s[2:3]
	global_load_dword v76, v[76:77], off
	s_add_i32 s2, s16, -13
	s_mov_b32 s3, s89
	v_pk_fma_f32 v[78:79], v[60:61], v[94:95], v[78:79]
	v_pk_fma_f32 v[84:85], v[58:59], v[94:95], v[84:85]
	v_pk_fma_f32 v[80:81], v[56:57], v[94:95], v[80:81]
	v_pk_fma_f32 v[86:87], v[54:55], v[94:95], v[86:87]
	v_pk_fma_f32 v[82:83], v[52:53], v[94:95], v[82:83]
	s_lshl_b64 s[2:3], s[2:3], 10
	s_waitcnt vmcnt(0)
; __device__ __forceinline__ void mix_a_wave_jobs(Frame& F, int l) {
;     ...
;                 const int s = s0 + hs, rowS = MP + 8 * s;
; #pragma unroll
;                 for (int tt = 0; tt < 38; ++tt) {
;                     f32x2 v;
;                     if (tt < 30) v = __builtin_nontemporal_load((const f32x2*)(st + ((size_t)s * 30 + tt) * DA + c0));
;                     else { const unsigned rw = *(const unsigned*)(U + (size_t)(rowS + tt - 30) * 512 + c0); v = (f32x2){__uint_as_float(rw << 16), __uint_as_float(rw & 0xffff0000u)}; }
; #pragma unroll
;                     for (int t = 0; t < 8; ++t) { const int kk = tt - t; if (kk >= 0 && kk <= 30) a[8 * hs + t] += w[kk] * v; }
	v_lshlrev_b32_e32 v94, 16, v76
	v_and_b32_e32 v95, 0xffff0000, v76
	v_pk_fma_f32 v[76:77], v[62:63], v[94:95], v[78:79]
	v_pk_fma_f32 v[78:79], v[60:61], v[94:95], v[84:85]
	v_pk_fma_f32 v[84:85], v[56:57], v[94:95], v[86:87]
	v_pk_fma_f32 v[86:87], v[52:53], v[94:95], v[88:89]
	v_pk_fma_f32 v[88:89], v[50:51], v[94:95], v[92:93]
	v_lshl_add_u64 v[92:93], v[70:71], 0, s[2:3]
	global_load_dword v93, v[92:93], off
	s_add_i32 s2, s16, -12
	s_mov_b32 s3, s89
	v_pk_fma_f32 v[80:81], v[58:59], v[94:95], v[80:81]
	v_pk_fma_f32 v[82:83], v[54:55], v[94:95], v[82:83]
	s_lshl_b64 s[2:3], s[2:3], 10
	s_waitcnt vmcnt(0)
	v_lshlrev_b32_e32 v92, 16, v93
	v_and_b32_e32 v93, 0xffff0000, v93
	v_pk_fma_f32 v[78:79], v[62:63], v[92:93], v[78:79]
	v_pk_fma_f32 v[80:81], v[60:61], v[92:93], v[80:81]
	v_pk_fma_f32 v[84:85], v[58:59], v[92:93], v[84:85]
	v_pk_fma_f32 v[82:83], v[56:57], v[92:93], v[82:83]
	v_pk_fma_f32 v[86:87], v[54:55], v[92:93], v[86:87]
	v_pk_fma_f32 v[88:89], v[52:53], v[92:93], v[88:89]
	v_lshl_add_u64 v[92:93], v[70:71], 0, s[2:3]
	global_load_dword v93, v[92:93], off
	s_add_i32 s2, s16, -11
	s_mov_b32 s3, s89
	s_lshl_b64 s[2:3], s[2:3], 10
	s_waitcnt vmcnt(0)
	v_lshlrev_b32_e32 v92, 16, v93
	v_and_b32_e32 v93, 0xffff0000, v93
	v_pk_fma_f32 v[94:95], v[58:59], v[92:93], v[82:83]
	v_lshl_add_u64 v[82:83], v[70:71], 0, s[2:3]
	global_load_dword v82, v[82:83], off
	s_add_i32 s2, s16, -10
	s_mov_b32 s3, s89
	v_pk_fma_f32 v[80:81], v[62:63], v[92:93], v[80:81]
	v_pk_fma_f32 v[84:85], v[60:61], v[92:93], v[84:85]
	v_pk_fma_f32 v[86:87], v[56:57], v[92:93], v[86:87]
	v_pk_fma_f32 v[88:89], v[54:55], v[92:93], v[88:89]
	s_lshl_b64 s[2:3], s[2:3], 10
	s_waitcnt vmcnt(0)
	v_lshlrev_b32_e32 v92, 16, v82
	v_and_b32_e32 v93, 0xffff0000, v82
	v_pk_fma_f32 v[82:83], v[62:63], v[92:93], v[84:85]
	v_pk_fma_f32 v[84:85], v[60:61], v[92:93], v[94:95]
	v_pk_fma_f32 v[86:87], v[58:59], v[92:93], v[86:87]
	v_pk_fma_f32 v[92:93], v[56:57], v[92:93], v[88:89]
	v_lshl_add_u64 v[88:89], v[70:71], 0, s[2:3]
	global_load_dword v88, v[88:89], off
	s_add_i32 s2, s16, -9
	s_mov_b32 s3, s89
	s_lshl_b64 s[2:3], s[2:3], 10
	s_waitcnt vmcnt(0)
	v_lshlrev_b32_e32 v94, 16, v88
	v_and_b32_e32 v95, 0xffff0000, v88
	v_pk_fma_f32 v[88:89], v[62:63], v[94:95], v[84:85]
	v_pk_fma_f32 v[84:85], v[60:61], v[94:95], v[86:87]
	v_lshl_add_u64 v[86:87], v[70:71], 0, s[2:3]
	global_load_dword v86, v[86:87], off
	s_add_i32 s2, s16, -8
	s_mov_b32 s3, s89
	v_pk_fma_f32 v[92:93], v[58:59], v[94:95], v[92:93]
	s_lshl_b64 s[2:3], s[2:3], 10
	s_waitcnt vmcnt(0)
	v_lshlrev_b32_e32 v94, 16, v86
	v_and_b32_e32 v95, 0xffff0000, v86
	v_pk_fma_f32 v[86:87], v[62:63], v[94:95], v[84:85]
	v_pk_fma_f32 v[84:85], v[60:61], v[94:95], v[92:93]
	v_lshl_add_u64 v[92:93], v[70:71], 0, s[2:3]
	global_load_dword v93, v[92:93], off
	s_add_i32 s2, s21, 1
	v_mad_u64_u32 v[90:91], s[2:3], s2, v208, v[90:91]
	v_add_co_u32_e32 v96, vcc, s85, v90
	global_load_dwordx2 v[94:95], v[90:91], off offset:2048 nt
	s_nop 0
	v_addc_co_u32_e32 v97, vcc, 0, v91, vcc
	v_add_co_u32_e32 v98, vcc, s17, v90
	global_load_dwordx2 v[96:97], v[96:97], off offset:2048 nt
	s_nop 0
	v_addc_co_u32_e32 v99, vcc, 0, v91, vcc
	v_add_co_u32_e32 v104, vcc, s19, v90
	global_load_dwordx2 v[100:101], v[98:99], off offset:-4096 nt
	s_nop 0
	v_addc_co_u32_e32 v105, vcc, 0, v91, vcc
	v_add_co_u32_e32 v106, vcc, s18, v90
	global_load_dwordx2 v[102:103], v[98:99], off nt
	s_nop 0
	v_addc_co_u32_e32 v107, vcc, 0, v91, vcc
	global_load_dwordx2 v[104:105], v[104:105], off offset:2048 nt
	s_add_i32 s2, s16, -7
	global_load_dwordx2 v[116:117], v[106:107], off nt
	global_load_dwordx2 v[108:109], v[106:107], off offset:-4096 nt
	s_mov_b32 s3, s89
	global_load_dwordx2 v[98:99], v[98:99], off offset:2048 nt
	s_lshl_b64 s[2:3], s[2:3], 10
	global_load_dwordx2 v[106:107], v[106:107], off offset:2048 nt
	s_mov_b32 s17, s89
	s_mov_b32 s18, s88
	s_waitcnt vmcnt(9)
	v_lshlrev_b32_e32 v92, 16, v93
	v_and_b32_e32 v93, 0xffff0000, v93
	v_pk_fma_f32 v[84:85], v[62:63], v[92:93], v[84:85]
	global_load_dwordx2 v[92:93], v[90:91], off nt
	s_waitcnt vmcnt(0)
	v_pk_fma_f32 v[92:93], v[2:3], v[92:93], v[64:65]
	s_nop 0
	v_pk_fma_f32 v[92:93], v[4:5], v[94:95], v[92:93]
	v_pk_fma_f32 v[94:95], v[2:3], v[94:95], v[64:65]
	v_pk_fma_f32 v[92:93], v[6:7], v[100:101], v[92:93]
	v_pk_fma_f32 v[94:95], v[4:5], v[100:101], v[94:95]
	v_pk_fma_f32 v[100:101], v[2:3], v[100:101], v[64:65]
	v_pk_fma_f32 v[92:93], v[8:9], v[96:97], v[92:93]
	v_pk_fma_f32 v[94:95], v[6:7], v[96:97], v[94:95]
	v_pk_fma_f32 v[100:101], v[4:5], v[96:97], v[100:101]
	v_pk_fma_f32 v[96:97], v[2:3], v[96:97], v[64:65]
	v_pk_fma_f32 v[92:93], v[10:11], v[102:103], v[92:93]
	v_pk_fma_f32 v[94:95], v[8:9], v[102:103], v[94:95]
	v_pk_fma_f32 v[100:101], v[6:7], v[102:103], v[100:101]
	v_pk_fma_f32 v[96:97], v[4:5], v[102:103], v[96:97]
	v_pk_fma_f32 v[102:103], v[2:3], v[102:103], v[64:65]
	v_pk_fma_f32 v[92:93], v[12:13], v[98:99], v[92:93]
	v_pk_fma_f32 v[94:95], v[10:11], v[98:99], v[94:95]
	v_pk_fma_f32 v[100:101], v[8:9], v[98:99], v[100:101]
	v_pk_fma_f32 v[96:97], v[6:7], v[98:99], v[96:97]
	v_pk_fma_f32 v[102:103], v[4:5], v[98:99], v[102:103]
	v_pk_fma_f32 v[98:99], v[2:3], v[98:99], v[64:65]
	v_pk_fma_f32 v[92:93], v[14:15], v[108:109], v[92:93]
	v_pk_fma_f32 v[94:95], v[12:13], v[108:109], v[94:95]
	v_pk_fma_f32 v[100:101], v[10:11], v[108:109], v[100:101]
	v_pk_fma_f32 v[96:97], v[8:9], v[108:109], v[96:97]
	v_pk_fma_f32 v[102:103], v[6:7], v[108:109], v[102:103]
	v_pk_fma_f32 v[98:99], v[4:5], v[108:109], v[98:99]
	v_pk_fma_f32 v[108:109], v[2:3], v[108:109], v[64:65]
	v_pk_fma_f32 v[92:93], v[16:17], v[104:105], v[92:93]
; __device__ __forceinline__ void mix_a_wave_jobs(Frame& F, int l) {
;     ...
;                 for (int tt = 0; tt < 38; ++tt) {
;                     f32x2 v;
;                     if (tt < 30) v = __builtin_nontemporal_load((const f32x2*)(st + ((size_t)s * 30 + tt) * DA + c0));
;                     else { const unsigned rw = *(const unsigned*)(U + (size_t)(rowS + tt - 30) * 512 + c0); v = (f32x2){__uint_as_float(rw << 16), __uint_as_float(rw & 0xffff0000u)}; }
; #pragma unroll
;                     for (int t = 0; t < 8; ++t) { const int kk = tt - t; if (kk >= 0 && kk <= 30) a[8 * hs + t] += w[kk] * v; }
	v_pk_fma_f32 v[94:95], v[14:15], v[104:105], v[94:95]
	v_pk_fma_f32 v[100:101], v[12:13], v[104:105], v[100:101]
	v_pk_fma_f32 v[96:97], v[10:11], v[104:105], v[96:97]
	v_pk_fma_f32 v[102:103], v[8:9], v[104:105], v[102:103]
	v_pk_fma_f32 v[98:99], v[6:7], v[104:105], v[98:99]
	v_pk_fma_f32 v[108:109], v[4:5], v[104:105], v[108:109]
	v_pk_fma_f32 v[104:105], v[2:3], v[104:105], v[64:65]
	v_pk_fma_f32 v[92:93], v[18:19], v[116:117], v[92:93]
	v_pk_fma_f32 v[94:95], v[16:17], v[116:117], v[94:95]
	v_pk_fma_f32 v[100:101], v[14:15], v[116:117], v[100:101]
	v_pk_fma_f32 v[96:97], v[12:13], v[116:117], v[96:97]
	v_pk_fma_f32 v[102:103], v[10:11], v[116:117], v[102:103]
	v_pk_fma_f32 v[98:99], v[8:9], v[116:117], v[98:99]
	v_pk_fma_f32 v[108:109], v[6:7], v[116:117], v[108:109]
	v_pk_fma_f32 v[104:105], v[4:5], v[116:117], v[104:105]
	v_pk_fma_f32 v[116:117], v[20:21], v[106:107], v[92:93]
	v_pk_fma_f32 v[94:95], v[18:19], v[106:107], v[94:95]
	v_pk_fma_f32 v[100:101], v[16:17], v[106:107], v[100:101]
	v_pk_fma_f32 v[96:97], v[14:15], v[106:107], v[96:97]
	v_pk_fma_f32 v[102:103], v[12:13], v[106:107], v[102:103]
	v_pk_fma_f32 v[98:99], v[10:11], v[106:107], v[98:99]
	v_pk_fma_f32 v[108:109], v[8:9], v[106:107], v[108:109]
	v_pk_fma_f32 v[104:105], v[6:7], v[106:107], v[104:105]
	v_add_co_u32_e32 v106, vcc, s23, v90
	s_nop 1
	v_addc_co_u32_e32 v107, vcc, 0, v91, vcc
	v_add_co_u32_e32 v92, vcc, s24, v90
	global_load_dwordx2 v[106:107], v[106:107], off offset:2048 nt
	s_nop 0
	v_addc_co_u32_e32 v93, vcc, 0, v91, vcc
	global_load_dwordx2 v[118:119], v[92:93], off offset:-4096 nt
	s_waitcnt vmcnt(0)
	v_pk_fma_f32 v[116:117], v[22:23], v[118:119], v[116:117]
	v_pk_fma_f32 v[94:95], v[20:21], v[118:119], v[94:95]
	v_pk_fma_f32 v[100:101], v[18:19], v[118:119], v[100:101]
	v_pk_fma_f32 v[96:97], v[16:17], v[118:119], v[96:97]
	v_pk_fma_f32 v[102:103], v[14:15], v[118:119], v[102:103]
	v_pk_fma_f32 v[98:99], v[12:13], v[118:119], v[98:99]
	v_pk_fma_f32 v[108:109], v[10:11], v[118:119], v[108:109]
	v_pk_fma_f32 v[104:105], v[8:9], v[118:119], v[104:105]
	v_pk_fma_f32 v[116:117], v[24:25], v[106:107], v[116:117]
	v_pk_fma_f32 v[94:95], v[22:23], v[106:107], v[94:95]
	v_pk_fma_f32 v[100:101], v[20:21], v[106:107], v[100:101]
	v_pk_fma_f32 v[96:97], v[18:19], v[106:107], v[96:97]
	v_pk_fma_f32 v[102:103], v[16:17], v[106:107], v[102:103]
	v_pk_fma_f32 v[98:99], v[14:15], v[106:107], v[98:99]
	v_pk_fma_f32 v[108:109], v[12:13], v[106:107], v[108:109]
	v_pk_fma_f32 v[104:105], v[10:11], v[106:107], v[104:105]
	global_load_dwordx2 v[106:107], v[92:93], off nt
	s_waitcnt vmcnt(0)
	v_pk_fma_f32 v[116:117], v[26:27], v[106:107], v[116:117]
	global_load_dwordx2 v[92:93], v[92:93], off offset:2048 nt
	v_pk_fma_f32 v[94:95], v[24:25], v[106:107], v[94:95]
	v_pk_fma_f32 v[100:101], v[22:23], v[106:107], v[100:101]
	v_pk_fma_f32 v[96:97], v[20:21], v[106:107], v[96:97]
	v_pk_fma_f32 v[102:103], v[18:19], v[106:107], v[102:103]
	v_pk_fma_f32 v[98:99], v[16:17], v[106:107], v[98:99]
	v_pk_fma_f32 v[108:109], v[14:15], v[106:107], v[108:109]
	v_pk_fma_f32 v[104:105], v[12:13], v[106:107], v[104:105]
	s_waitcnt vmcnt(0)
	v_pk_fma_f32 v[106:107], v[28:29], v[92:93], v[116:117]
	v_pk_fma_f32 v[94:95], v[26:27], v[92:93], v[94:95]
	v_pk_fma_f32 v[100:101], v[24:25], v[92:93], v[100:101]
	v_pk_fma_f32 v[96:97], v[22:23], v[92:93], v[96:97]
	v_pk_fma_f32 v[102:103], v[20:21], v[92:93], v[102:103]
	v_pk_fma_f32 v[98:99], v[18:19], v[92:93], v[98:99]
	v_pk_fma_f32 v[108:109], v[16:17], v[92:93], v[108:109]
	v_pk_fma_f32 v[92:93], v[14:15], v[92:93], v[104:105]
	v_add_co_u32_e32 v104, vcc, s25, v90
	s_nop 1
	v_addc_co_u32_e32 v105, vcc, 0, v91, vcc
	v_add_co_u32_e32 v116, vcc, s26, v90
	global_load_dwordx2 v[104:105], v[104:105], off offset:2048 nt
	s_nop 0
	v_addc_co_u32_e32 v117, vcc, 0, v91, vcc
	global_load_dwordx2 v[118:119], v[116:117], off offset:-4096 nt
	s_waitcnt vmcnt(0)
	v_pk_fma_f32 v[106:107], v[30:31], v[118:119], v[106:107]
	v_pk_fma_f32 v[94:95], v[28:29], v[118:119], v[94:95]
	v_pk_fma_f32 v[100:101], v[26:27], v[118:119], v[100:101]
	v_pk_fma_f32 v[96:97], v[24:25], v[118:119], v[96:97]
	v_pk_fma_f32 v[102:103], v[22:23], v[118:119], v[102:103]
	v_pk_fma_f32 v[98:99], v[20:21], v[118:119], v[98:99]
	v_pk_fma_f32 v[108:109], v[18:19], v[118:119], v[108:109]
	v_pk_fma_f32 v[92:93], v[16:17], v[118:119], v[92:93]
	v_pk_fma_f32 v[106:107], v[32:33], v[104:105], v[106:107]
	v_pk_fma_f32 v[94:95], v[30:31], v[104:105], v[94:95]
	v_pk_fma_f32 v[100:101], v[28:29], v[104:105], v[100:101]
	v_pk_fma_f32 v[96:97], v[26:27], v[104:105], v[96:97]
	v_pk_fma_f32 v[102:103], v[24:25], v[104:105], v[102:103]
	v_pk_fma_f32 v[98:99], v[22:23], v[104:105], v[98:99]
	v_pk_fma_f32 v[108:109], v[20:21], v[104:105], v[108:109]
	v_pk_fma_f32 v[92:93], v[18:19], v[104:105], v[92:93]
	global_load_dwordx2 v[104:105], v[116:117], off nt
	s_waitcnt vmcnt(0)
	v_pk_fma_f32 v[106:107], v[34:35], v[104:105], v[106:107]
	v_pk_fma_f32 v[94:95], v[32:33], v[104:105], v[94:95]
	v_pk_fma_f32 v[100:101], v[30:31], v[104:105], v[100:101]
	v_pk_fma_f32 v[96:97], v[28:29], v[104:105], v[96:97]
	v_pk_fma_f32 v[102:103], v[26:27], v[104:105], v[102:103]
	v_pk_fma_f32 v[98:99], v[24:25], v[104:105], v[98:99]
	v_pk_fma_f32 v[108:109], v[22:23], v[104:105], v[108:109]
	v_pk_fma_f32 v[92:93], v[20:21], v[104:105], v[92:93]
	global_load_dwordx2 v[104:105], v[116:117], off offset:2048 nt
	s_waitcnt vmcnt(0)
; __device__ __forceinline__ void mix_a_wave_jobs(Frame& F, int l) {
;     ...
;                 for (int tt = 0; tt < 38; ++tt) {
;                     f32x2 v;
;                     if (tt < 30) v = __builtin_nontemporal_load((const f32x2*)(st + ((size_t)s * 30 + tt) * DA + c0));
;                     else { const unsigned rw = *(const unsigned*)(U + (size_t)(rowS + tt - 30) * 512 + c0); v = (f32x2){__uint_as_float(rw << 16), __uint_as_float(rw & 0xffff0000u)}; }
; #pragma unroll
;                     for (int t = 0; t < 8; ++t) { const int kk = tt - t; if (kk >= 0 && kk <= 30) a[8 * hs + t] += w[kk] * v; }
	v_pk_fma_f32 v[106:107], v[36:37], v[104:105], v[106:107]
	v_pk_fma_f32 v[94:95], v[34:35], v[104:105], v[94:95]
	v_pk_fma_f32 v[100:101], v[32:33], v[104:105], v[100:101]
	v_pk_fma_f32 v[96:97], v[30:31], v[104:105], v[96:97]
	v_pk_fma_f32 v[102:103], v[28:29], v[104:105], v[102:103]
	v_pk_fma_f32 v[98:99], v[26:27], v[104:105], v[98:99]
	v_pk_fma_f32 v[108:109], v[24:25], v[104:105], v[108:109]
	v_pk_fma_f32 v[92:93], v[22:23], v[104:105], v[92:93]
	v_add_co_u32_e32 v104, vcc, s27, v90
	s_nop 1
	v_addc_co_u32_e32 v105, vcc, 0, v91, vcc
	v_add_co_u32_e32 v116, vcc, s28, v90
	global_load_dwordx2 v[104:105], v[104:105], off offset:2048 nt
	s_nop 0
	v_addc_co_u32_e32 v117, vcc, 0, v91, vcc
	global_load_dwordx2 v[118:119], v[116:117], off offset:-4096 nt
	s_waitcnt vmcnt(0)
	v_pk_fma_f32 v[106:107], v[38:39], v[118:119], v[106:107]
	v_pk_fma_f32 v[94:95], v[36:37], v[118:119], v[94:95]
	v_pk_fma_f32 v[100:101], v[34:35], v[118:119], v[100:101]
	v_pk_fma_f32 v[96:97], v[32:33], v[118:119], v[96:97]
	v_pk_fma_f32 v[102:103], v[30:31], v[118:119], v[102:103]
	v_pk_fma_f32 v[98:99], v[28:29], v[118:119], v[98:99]
	v_pk_fma_f32 v[108:109], v[26:27], v[118:119], v[108:109]
	v_pk_fma_f32 v[92:93], v[24:25], v[118:119], v[92:93]
	v_pk_fma_f32 v[106:107], v[40:41], v[104:105], v[106:107]
	v_pk_fma_f32 v[94:95], v[38:39], v[104:105], v[94:95]
	v_pk_fma_f32 v[100:101], v[36:37], v[104:105], v[100:101]
	v_pk_fma_f32 v[96:97], v[34:35], v[104:105], v[96:97]
	v_pk_fma_f32 v[102:103], v[32:33], v[104:105], v[102:103]
	v_pk_fma_f32 v[98:99], v[30:31], v[104:105], v[98:99]
	v_pk_fma_f32 v[108:109], v[28:29], v[104:105], v[108:109]
	v_pk_fma_f32 v[92:93], v[26:27], v[104:105], v[92:93]
	global_load_dwordx2 v[104:105], v[116:117], off nt
	s_waitcnt vmcnt(0)
	v_pk_fma_f32 v[106:107], v[42:43], v[104:105], v[106:107]
	v_pk_fma_f32 v[94:95], v[40:41], v[104:105], v[94:95]
	v_pk_fma_f32 v[100:101], v[38:39], v[104:105], v[100:101]
	v_pk_fma_f32 v[96:97], v[36:37], v[104:105], v[96:97]
	v_pk_fma_f32 v[102:103], v[34:35], v[104:105], v[102:103]
	v_pk_fma_f32 v[98:99], v[32:33], v[104:105], v[98:99]
	v_pk_fma_f32 v[108:109], v[30:31], v[104:105], v[108:109]
	v_pk_fma_f32 v[92:93], v[28:29], v[104:105], v[92:93]
	global_load_dwordx2 v[104:105], v[116:117], off offset:2048 nt
	v_add_co_u32_e32 v116, vcc, s29, v90
	s_waitcnt vmcnt(0)
	v_pk_fma_f32 v[106:107], v[44:45], v[104:105], v[106:107]
	v_addc_co_u32_e32 v117, vcc, 0, v91, vcc
	v_pk_fma_f32 v[94:95], v[42:43], v[104:105], v[94:95]
	v_pk_fma_f32 v[100:101], v[40:41], v[104:105], v[100:101]
	v_pk_fma_f32 v[96:97], v[38:39], v[104:105], v[96:97]
	v_pk_fma_f32 v[102:103], v[36:37], v[104:105], v[102:103]
	v_pk_fma_f32 v[98:99], v[34:35], v[104:105], v[98:99]
	v_pk_fma_f32 v[108:109], v[32:33], v[104:105], v[108:109]
	v_pk_fma_f32 v[104:105], v[30:31], v[104:105], v[92:93]
	v_add_co_u32_e32 v92, vcc, s30, v90
	global_load_dwordx2 v[116:117], v[116:117], off offset:2048 nt
	s_nop 0
	v_addc_co_u32_e32 v93, vcc, 0, v91, vcc
	global_load_dwordx2 v[118:119], v[92:93], off offset:-4096 nt
	s_waitcnt vmcnt(0)
	v_pk_fma_f32 v[106:107], v[46:47], v[118:119], v[106:107]
	v_pk_fma_f32 v[94:95], v[44:45], v[118:119], v[94:95]
	v_pk_fma_f32 v[100:101], v[42:43], v[118:119], v[100:101]
	v_pk_fma_f32 v[96:97], v[40:41], v[118:119], v[96:97]
	v_pk_fma_f32 v[102:103], v[38:39], v[118:119], v[102:103]
	v_pk_fma_f32 v[98:99], v[36:37], v[118:119], v[98:99]
	v_pk_fma_f32 v[108:109], v[34:35], v[118:119], v[108:109]
	v_pk_fma_f32 v[104:105], v[32:33], v[118:119], v[104:105]
	v_pk_fma_f32 v[106:107], v[48:49], v[116:117], v[106:107]
	v_pk_fma_f32 v[94:95], v[46:47], v[116:117], v[94:95]
	v_pk_fma_f32 v[100:101], v[44:45], v[116:117], v[100:101]
	v_pk_fma_f32 v[96:97], v[42:43], v[116:117], v[96:97]
	v_pk_fma_f32 v[102:103], v[40:41], v[116:117], v[102:103]
	v_pk_fma_f32 v[98:99], v[38:39], v[116:117], v[98:99]
	v_pk_fma_f32 v[108:109], v[36:37], v[116:117], v[108:109]
	v_pk_fma_f32 v[104:105], v[34:35], v[116:117], v[104:105]
	global_load_dwordx2 v[116:117], v[92:93], off nt
	s_waitcnt vmcnt(0)
	v_pk_fma_f32 v[106:107], v[50:51], v[116:117], v[106:107]
	global_load_dwordx2 v[92:93], v[92:93], off offset:2048 nt
	v_pk_fma_f32 v[94:95], v[48:49], v[116:117], v[94:95]
	v_pk_fma_f32 v[100:101], v[46:47], v[116:117], v[100:101]
	v_pk_fma_f32 v[96:97], v[44:45], v[116:117], v[96:97]
	v_pk_fma_f32 v[102:103], v[42:43], v[116:117], v[102:103]
	v_pk_fma_f32 v[98:99], v[40:41], v[116:117], v[98:99]
	v_pk_fma_f32 v[108:109], v[38:39], v[116:117], v[108:109]
	v_pk_fma_f32 v[104:105], v[36:37], v[116:117], v[104:105]
	s_waitcnt vmcnt(0)
	v_pk_fma_f32 v[106:107], v[52:53], v[92:93], v[106:107]
	v_pk_fma_f32 v[94:95], v[50:51], v[92:93], v[94:95]
	v_pk_fma_f32 v[100:101], v[48:49], v[92:93], v[100:101]
	v_pk_fma_f32 v[96:97], v[46:47], v[92:93], v[96:97]
	v_pk_fma_f32 v[102:103], v[44:45], v[92:93], v[102:103]
	v_pk_fma_f32 v[98:99], v[42:43], v[92:93], v[98:99]
	v_pk_fma_f32 v[108:109], v[40:41], v[92:93], v[108:109]
	v_pk_fma_f32 v[92:93], v[38:39], v[92:93], v[104:105]
	v_add_co_u32_e32 v104, vcc, s31, v90
	s_nop 1
	v_addc_co_u32_e32 v105, vcc, 0, v91, vcc
	v_add_co_u32_e32 v90, vcc, s34, v90
	global_load_dwordx2 v[104:105], v[104:105], off offset:2048 nt
	s_nop 0
	v_addc_co_u32_e32 v91, vcc, 0, v91, vcc
	global_load_dwordx2 v[116:117], v[90:91], off offset:-4096 nt
	s_waitcnt vmcnt(0)
; __device__ __forceinline__ void mix_a_wave_jobs(Frame& F, int l) {
;     ...
;                 for (int tt = 0; tt < 38; ++tt) {
;                     f32x2 v;
;                     if (tt < 30) v = __builtin_nontemporal_load((const f32x2*)(st + ((size_t)s * 30 + tt) * DA + c0));
;                     else { const unsigned rw = *(const unsigned*)(U + (size_t)(rowS + tt - 30) * 512 + c0); v = (f32x2){__uint_as_float(rw << 16), __uint_as_float(rw & 0xffff0000u)}; }
; #pragma unroll
;                     for (int t = 0; t < 8; ++t) { const int kk = tt - t; if (kk >= 0 && kk <= 30) a[8 * hs + t] += w[kk] * v; }
;                 }
;             }
	v_pk_fma_f32 v[106:107], v[54:55], v[116:117], v[106:107]
	v_pk_fma_f32 v[94:95], v[52:53], v[116:117], v[94:95]
	v_pk_fma_f32 v[100:101], v[50:51], v[116:117], v[100:101]
	v_pk_fma_f32 v[96:97], v[48:49], v[116:117], v[96:97]
	v_pk_fma_f32 v[102:103], v[46:47], v[116:117], v[102:103]
	v_pk_fma_f32 v[98:99], v[44:45], v[116:117], v[98:99]
	v_pk_fma_f32 v[108:109], v[42:43], v[116:117], v[108:109]
	v_pk_fma_f32 v[92:93], v[40:41], v[116:117], v[92:93]
	v_pk_fma_f32 v[106:107], v[56:57], v[104:105], v[106:107]
	v_pk_fma_f32 v[94:95], v[54:55], v[104:105], v[94:95]
	v_pk_fma_f32 v[100:101], v[52:53], v[104:105], v[100:101]
	v_pk_fma_f32 v[96:97], v[50:51], v[104:105], v[96:97]
	v_pk_fma_f32 v[102:103], v[48:49], v[104:105], v[102:103]
	v_pk_fma_f32 v[98:99], v[46:47], v[104:105], v[98:99]
	v_pk_fma_f32 v[108:109], v[44:45], v[104:105], v[108:109]
	v_pk_fma_f32 v[92:93], v[42:43], v[104:105], v[92:93]
	global_load_dwordx2 v[104:105], v[90:91], off nt
	s_waitcnt vmcnt(0)
	v_pk_fma_f32 v[106:107], v[58:59], v[104:105], v[106:107]
	global_load_dwordx2 v[90:91], v[90:91], off offset:2048 nt
	v_pk_fma_f32 v[94:95], v[56:57], v[104:105], v[94:95]
	v_pk_fma_f32 v[100:101], v[54:55], v[104:105], v[100:101]
	v_pk_fma_f32 v[96:97], v[52:53], v[104:105], v[96:97]
	v_pk_fma_f32 v[102:103], v[50:51], v[104:105], v[102:103]
	v_pk_fma_f32 v[98:99], v[48:49], v[104:105], v[98:99]
	v_pk_fma_f32 v[108:109], v[46:47], v[104:105], v[108:109]
	v_pk_fma_f32 v[92:93], v[44:45], v[104:105], v[92:93]
	s_waitcnt vmcnt(0)
	v_pk_fma_f32 v[104:105], v[60:61], v[90:91], v[106:107]
	v_pk_fma_f32 v[94:95], v[58:59], v[90:91], v[94:95]
	v_pk_fma_f32 v[100:101], v[56:57], v[90:91], v[100:101]
	v_pk_fma_f32 v[96:97], v[54:55], v[90:91], v[96:97]
	v_pk_fma_f32 v[102:103], v[52:53], v[90:91], v[102:103]
	v_pk_fma_f32 v[98:99], v[50:51], v[90:91], v[98:99]
	v_pk_fma_f32 v[106:107], v[48:49], v[90:91], v[108:109]
	v_pk_fma_f32 v[92:93], v[46:47], v[90:91], v[92:93]
	v_lshl_add_u64 v[90:91], v[70:71], 0, s[2:3]
	global_load_dword v90, v[90:91], off
	s_add_i32 s2, s16, -6
	s_mov_b32 s3, s89
	s_lshl_b64 s[2:3], s[2:3], 10
	s_waitcnt vmcnt(0)
	v_lshlrev_b32_e32 v108, 16, v90
	v_and_b32_e32 v109, 0xffff0000, v90
	v_pk_fma_f32 v[90:91], v[62:63], v[108:109], v[104:105]
	v_pk_fma_f32 v[104:105], v[50:51], v[108:109], v[106:107]
	v_pk_fma_f32 v[106:107], v[48:49], v[108:109], v[92:93]
	v_lshl_add_u64 v[92:93], v[70:71], 0, s[2:3]
	global_load_dword v92, v[92:93], off
	s_add_i32 s2, s16, -5
	s_mov_b32 s3, s89
	v_pk_fma_f32 v[94:95], v[60:61], v[108:109], v[94:95]
	v_pk_fma_f32 v[100:101], v[58:59], v[108:109], v[100:101]
	v_pk_fma_f32 v[96:97], v[56:57], v[108:109], v[96:97]
	v_pk_fma_f32 v[102:103], v[54:55], v[108:109], v[102:103]
	v_pk_fma_f32 v[98:99], v[52:53], v[108:109], v[98:99]
	s_lshl_b64 s[2:3], s[2:3], 10
	s_waitcnt vmcnt(0)
	v_lshlrev_b32_e32 v108, 16, v92
	v_and_b32_e32 v109, 0xffff0000, v92
	v_pk_fma_f32 v[92:93], v[62:63], v[108:109], v[94:95]
	v_pk_fma_f32 v[94:95], v[60:61], v[108:109], v[100:101]
	v_pk_fma_f32 v[100:101], v[56:57], v[108:109], v[102:103]
	v_pk_fma_f32 v[102:103], v[52:53], v[108:109], v[104:105]
	v_pk_fma_f32 v[104:105], v[50:51], v[108:109], v[106:107]
	v_lshl_add_u64 v[106:107], v[70:71], 0, s[2:3]
	global_load_dword v107, v[106:107], off
	s_add_i32 s2, s16, -4
	s_mov_b32 s3, s89
	v_pk_fma_f32 v[98:99], v[54:55], v[108:109], v[98:99]
	s_lshl_b64 s[2:3], s[2:3], 10
	v_pk_fma_f32 v[96:97], v[58:59], v[108:109], v[96:97]
	s_waitcnt vmcnt(0)
	v_lshlrev_b32_e32 v106, 16, v107
	v_and_b32_e32 v107, 0xffff0000, v107
	v_pk_fma_f32 v[108:109], v[56:57], v[106:107], v[98:99]
	v_lshl_add_u64 v[98:99], v[70:71], 0, s[2:3]
	global_load_dword v98, v[98:99], off
	s_add_i32 s2, s16, -3
	s_mov_b32 s3, s89
	v_pk_fma_f32 v[94:95], v[62:63], v[106:107], v[94:95]
	v_pk_fma_f32 v[96:97], v[60:61], v[106:107], v[96:97]
	v_pk_fma_f32 v[100:101], v[58:59], v[106:107], v[100:101]
	v_pk_fma_f32 v[102:103], v[54:55], v[106:107], v[102:103]
	v_pk_fma_f32 v[104:105], v[52:53], v[106:107], v[104:105]
	s_lshl_b64 s[2:3], s[2:3], 10
	s_waitcnt vmcnt(0)
	v_lshlrev_b32_e32 v106, 16, v98
	v_and_b32_e32 v107, 0xffff0000, v98
	v_pk_fma_f32 v[98:99], v[62:63], v[106:107], v[96:97]
	v_pk_fma_f32 v[96:97], v[60:61], v[106:107], v[100:101]
	v_pk_fma_f32 v[100:101], v[58:59], v[106:107], v[108:109]
	v_pk_fma_f32 v[102:103], v[56:57], v[106:107], v[102:103]
	v_pk_fma_f32 v[104:105], v[54:55], v[106:107], v[104:105]
	v_lshl_add_u64 v[106:107], v[70:71], 0, s[2:3]
	global_load_dword v107, v[106:107], off
	s_add_i32 s2, s16, -2
	s_mov_b32 s3, s89
	s_lshl_b64 s[2:3], s[2:3], 10
	s_waitcnt vmcnt(0)
	v_lshlrev_b32_e32 v106, 16, v107
	v_and_b32_e32 v107, 0xffff0000, v107
	v_pk_fma_f32 v[96:97], v[62:63], v[106:107], v[96:97]
	v_pk_fma_f32 v[100:101], v[60:61], v[106:107], v[100:101]
	v_pk_fma_f32 v[102:103], v[58:59], v[106:107], v[102:103]
	v_pk_fma_f32 v[104:105], v[56:57], v[106:107], v[104:105]
	v_lshl_add_u64 v[106:107], v[70:71], 0, s[2:3]
	global_load_dword v107, v[106:107], off
	s_add_i32 s2, s16, -1
	s_mov_b32 s3, s89
	s_lshl_b64 s[2:3], s[2:3], 10
	s_waitcnt vmcnt(0)
	v_lshlrev_b32_e32 v106, 16, v107
	v_and_b32_e32 v107, 0xffff0000, v107
	v_pk_fma_f32 v[100:101], v[62:63], v[106:107], v[100:101]
	v_pk_fma_f32 v[102:103], v[60:61], v[106:107], v[102:103]
	v_pk_fma_f32 v[104:105], v[58:59], v[106:107], v[104:105]
	v_lshl_add_u64 v[106:107], v[70:71], 0, s[2:3]
	global_load_dword v107, v[106:107], off
	s_lshl_b64 s[2:3], s[16:17], 10
	s_waitcnt vmcnt(0)
	v_lshlrev_b32_e32 v106, 16, v107
	v_and_b32_e32 v107, 0xffff0000, v107
	v_pk_fma_f32 v[102:103], v[62:63], v[106:107], v[102:103]
	v_pk_fma_f32 v[104:105], v[60:61], v[106:107], v[104:105]
	v_lshl_add_u64 v[106:107], v[70:71], 0, s[2:3]
	global_load_dword v106, v[106:107], off
	s_cbranch_execz .LBB0_273
	s_branch .LBB0_276
